# m1 per-lane address registers hoisted out of the chunk loop as well
# baseline (speedup 1.0000x reference)
.LBB0_284:
	s_or_b64 exec, exec, s[0:1]
	s_mov_b64 s[0:1], s[72:73]
	v_readlane_b32 s4, v254, 35
	v_readlane_b32 s2, v254, 60
	s_and_b64 vcc, exec, s[58:59]
	s_waitcnt lgkmcnt(0)
	s_barrier
	v_readlane_b32 s3, v254, 61
	s_cbranch_vccz .LBB0_305
	s_load_dwordx2 s[6:7], s[0:1], 0x88
	s_load_dwordx8 s[8:15], s[0:1], 0x48
	s_mov_b32 s26, s70
	s_waitcnt lgkmcnt(0)
	s_add_u32 s0, s6, 0xc000000
	s_addc_u32 s1, s7, 0
	s_add_u32 s22, s6, 0xe000000
	s_addc_u32 s23, s7, 0
	s_lshl_b32 s2, s4, 12
	s_ashr_i32 s3, s2, 31
	s_lshl_b64 s[2:3], s[2:3], 2
	s_add_u32 s2, s8, s2
	s_addc_u32 s3, s9, s3
	s_lshl_b32 s8, s4, 10
	s_ashr_i32 s9, s8, 31
	s_lshl_b64 s[8:9], s[8:9], 2
	s_add_u32 s8, s10, s8
	s_addc_u32 s9, s11, s9
	s_lshl_b32 s4, s4, 3
	s_ashr_i32 s5, s4, 31
	s_lshl_b64 s[4:5], s[4:5], 2
	s_add_u32 s10, s14, s4
	s_addc_u32 s11, s15, s5
	s_add_u32 s12, s12, s4
	s_addc_u32 s13, s13, s5
	s_add_u32 s14, s6, 0x18000000
	s_addc_u32 s15, s7, 0
	s_add_u32 s24, s6, 0x18100000
	s_addc_u32 s25, s7, 0
	v_readlane_b32 s4, v254, 31
	s_add_u32 s16, s6, s4
	v_readlane_b32 s4, v254, 32
	s_addc_u32 s17, s7, s4
	v_readlane_b32 s4, v254, 33
	s_mov_b32 s18, s4
	v_lshlrev_b32_e32 v0, 4, v194
	global_load_dwordx4 v[4:7], v0, s[2:3]
	s_add_u32 s90, s2, 0x2000
	s_addc_u32 s91, s3, 0
	global_load_dwordx4 v[8:11], v0, s[90:91]
	v_cmp_gt_u32_e32 vcc, 0x100, v194
	s_and_saveexec_b64 s[92:93], vcc
	global_load_dwordx4 v[12:15], v0, s[8:9]
	s_mov_b64 exec, s[92:93]
	v_add_u32_e32 v1, 0x1a000, v0
	s_waitcnt vmcnt(0)
	ds_write_b128 v1, v[4:7]
	ds_write_b128 v1, v[8:11] offset:8192
	s_and_saveexec_b64 s[92:93], vcc
	ds_write_b128 v1, v[12:15] offset:16384
	s_mov_b64 exec, s[92:93]
	s_waitcnt lgkmcnt(0)
	s_barrier
	v_lshrrev_b32_e32 v209, 3, v194
	v_and_b32_e32 v210, 7, v194
	v_lshlrev_b32_e32 v211, 4, v210
	v_lshl_or_b32 v190, v209, 15, v211
	v_lshl_or_b32 v192, v209, 11, v211
	v_add_u32_e32 v193, 0x1000, v192
	v_lshlrev_b32_e32 v208, 5, v210
	s_branch .LBB0_288

.LBB0_288:
	s_ashr_i32 s4, s26, 10
	s_and_b32 s28, s26, 0x7f
	s_ashr_i32 s5, s4, 31
	v_mov_b32_e32 v15, v194
	s_lshl_b64 s[20:21], s[4:5], 13
	s_lshl_b32 s4, s28, 6
	s_bfe_u32 s29, s26, 0x30007
	v_and_b32_e32 v14, 63, v15
	v_readfirstlane_b32 s27, v15
	s_or_b32 s20, s20, s4
	s_lshl_b32 s90, s29, 7
	s_or_b32 s90, s90, 0x400
	s_lshl_b64 s[52:53], s[20:21], 1
	s_add_u32 s52, s22, s52
	s_addc_u32 s53, s23, s53
	s_lshl_b32 s91, s90, 15
	s_add_u32 s52, s52, s91
	s_addc_u32 s53, s53, 0
	s_add_u32 s54, s52, 0x200000
	s_addc_u32 s55, s53, 0
	global_load_dwordx4 v[44:47], v190, s[52:53]
	global_load_dwordx4 v[48:51], v190, s[54:55]
	s_sub_u32 s92, s20, 3
	s_subb_u32 s93, s21, 0
	s_lshl_b64 s[92:93], s[92:93], 11
	s_add_u32 s92, s0, s92
	s_addc_u32 s93, s1, s93
	s_lshl_b32 s91, s29, 7
	s_add_u32 s92, s92, s91
	s_addc_u32 s93, s93, 0
	s_cmp_lg_u32 s28, 0
	s_cselect_b64 s[54:55], -1, 0
	v_cmp_lt_u32_e32 vcc, 2, v209
	s_or_b64 s[46:47], s[54:55], vcc
	v_cmp_lt_u32_e32 vcc, 1, v209
	s_or_b64 s[48:49], s[54:55], vcc
	v_cmp_lt_u32_e32 vcc, 0, v209
	s_or_b64 s[50:51], s[54:55], vcc
	s_mov_b64 s[96:97], exec
	s_and_b64 exec, s[96:97], s[46:47]
	global_load_dwordx4 v[80:83], v192, s[92:93] offset:1024
	s_and_b64 exec, s[96:97], s[48:49]
	global_load_dwordx4 v[92:95], v192, s[92:93] offset:3072
	s_and_b64 exec, s[96:97], s[50:51]
	global_load_dwordx4 v[104:107], v193, s[92:93] offset:1024
	s_mov_b64 exec, s[96:97]
	global_load_dwordx4 v[116:119], v193, s[92:93] offset:3072
	s_cmp_gt_u32 s27, 63
	v_cmp_gt_u32_e32 vcc, 16, v14
	s_cbranch_scc1 .LBB0_292
	v_or_b32_e32 v0, s20, v14
	v_mov_b32_e32 v1, s21
	v_lshlrev_b64 v[0:1], 6, v[0:1]
	v_lshl_add_u64 v[0:1], s[14:15], 0, v[0:1]
	s_lshl_b32 s86, s29, 2
	v_lshl_add_u64 v[0:1], v[0:1], 0, s[86:87]
	v_mov_b32_e32 v3, s86
	global_load_dword v2, v[0:1], off offset:32
	global_load_dword v4, v3, s[10:11]
	s_nop 0
	global_load_dword v0, v[0:1], off
	s_nop 0
	global_load_dword v1, v3, s[12:13]
	s_waitcnt vmcnt(2)
	v_add_f32_e32 v2, v2, v4
	s_waitcnt vmcnt(0)
	v_add_f32_e32 v0, v0, v1
	v_min_f32_e32 v1, 0, v2
	v_mul_f32_e64 v2, |v2|, s79
	v_exp_f32_e32 v4, v2
	s_nop 0
	v_add_f32_e32 v5, 1.0, v4
	v_add_f32_e32 v2, -1.0, v5
	v_sub_f32_e32 v3, v2, v5
	v_add_f32_e32 v3, 1.0, v3
	v_sub_f32_e32 v2, v4, v2
	v_add_f32_e32 v6, v2, v3
	v_frexp_mant_f32_e32 v2, v5
	v_cmp_gt_f32_e64 s[4:5], s85, v2
	v_cvt_f64_f32_e32 v[2:3], v5
	v_frexp_exp_i32_f64_e32 v2, v[2:3]
	v_subbrev_co_u32_e64 v2, s[4:5], 0, v2, s[4:5]
	v_sub_u32_e32 v3, 0, v2
	v_ldexp_f32 v5, v5, v3
	v_ldexp_f32 v3, v6, v3
	v_add_f32_e32 v6, -1.0, v5
	v_add_f32_e32 v7, 1.0, v6
	v_sub_f32_e32 v7, v5, v7
	v_add_f32_e32 v7, v3, v7
	v_add_f32_e32 v8, v6, v7
	v_sub_f32_e32 v6, v8, v6
	v_sub_f32_e32 v6, v7, v6
	v_add_f32_e32 v7, 1.0, v5
	v_add_f32_e32 v9, -1.0, v7
	v_sub_f32_e32 v5, v5, v9
	v_add_f32_e32 v3, v3, v5
	v_add_f32_e32 v5, v7, v3
	v_sub_f32_e32 v7, v5, v7
	v_sub_f32_e32 v3, v3, v7
	v_rcp_f32_e32 v7, v5
	v_cvt_f32_i32_e32 v2, v2
	s_mov_b32 s4, 0x3f317218
	v_mul_f32_e32 v9, v8, v7
	v_mul_f32_e32 v10, v5, v9
	v_fma_f32 v11, v9, v5, -v10
	v_fmac_f32_e32 v11, v9, v3
	v_add_f32_e32 v12, v10, v11
	v_sub_f32_e32 v13, v8, v12
	v_sub_f32_e32 v8, v8, v13
	v_sub_f32_e32 v10, v12, v10
	v_sub_f32_e32 v8, v8, v12
	v_add_f32_e32 v6, v6, v8
	v_sub_f32_e32 v8, v10, v11
	v_add_f32_e32 v6, v8, v6
	v_add_f32_e32 v8, v13, v6
	v_mul_f32_e32 v10, v7, v8
	v_mul_f32_e32 v11, v5, v10
	v_fma_f32 v5, v10, v5, -v11
	v_fmac_f32_e32 v5, v10, v3
	v_sub_f32_e32 v3, v13, v8
	v_add_f32_e32 v3, v6, v3
	v_add_f32_e32 v6, v11, v5
	v_sub_f32_e32 v12, v8, v6
	v_sub_f32_e32 v8, v8, v12
	v_sub_f32_e32 v11, v6, v11
	v_sub_f32_e32 v6, v8, v6
	v_add_f32_e32 v3, v3, v6
	v_sub_f32_e32 v5, v11, v5
	v_add_f32_e32 v3, v5, v3
	v_add_f32_e32 v5, v9, v10
	v_add_f32_e32 v3, v12, v3
	v_sub_f32_e32 v6, v5, v9
	v_mul_f32_e32 v3, v7, v3
	v_sub_f32_e32 v6, v10, v6
	v_add_f32_e32 v3, v6, v3
	v_mul_f32_e32 v9, 0x3f317218, v2
	v_add_f32_e32 v6, v5, v3
	v_fma_f32 v10, v2, s4, -v9
	v_mul_f32_e32 v7, v6, v6
	v_fmac_f32_e32 v10, 0xb102e308, v2
	v_sub_f32_e32 v2, v6, v5
	v_fmamk_f32 v8, v7, 0x3e9b6dac, v200
	v_sub_f32_e32 v2, v3, v2
	v_add_f32_e32 v3, v9, v10
	v_fmaak_f32 v8, v7, v8, 0x3f2aaada
	v_sub_f32_e32 v5, v3, v9
	v_ldexp_f32 v9, v6, 1
	v_mul_f32_e32 v6, v6, v7
	v_mul_f32_e32 v6, v6, v8
	v_add_f32_e32 v7, v9, v6
	v_sub_f32_e32 v8, v7, v9
	v_ldexp_f32 v2, v2, 1
	v_sub_f32_e32 v6, v6, v8
	v_add_f32_e32 v2, v2, v6
	v_add_f32_e32 v6, v7, v2
	v_sub_f32_e32 v7, v6, v7
	v_sub_f32_e32 v2, v2, v7
	v_add_f32_e32 v7, v3, v6
	v_sub_f32_e32 v8, v7, v3
	v_sub_f32_e32 v9, v7, v8
	v_sub_f32_e32 v5, v10, v5
	v_sub_f32_e32 v3, v3, v9
	v_sub_f32_e32 v6, v6, v8
	v_add_f32_e32 v3, v6, v3
	v_add_f32_e32 v6, v5, v2
	v_sub_f32_e32 v8, v6, v5
	v_sub_f32_e32 v9, v6, v8
	v_sub_f32_e32 v5, v5, v9
	v_sub_f32_e32 v2, v2, v8
	v_add_f32_e32 v3, v6, v3
	v_add_f32_e32 v2, v2, v5
	v_add_f32_e32 v5, v7, v3
	v_sub_f32_e32 v6, v5, v7
	v_sub_f32_e32 v3, v3, v6
	v_add_f32_e32 v2, v2, v3
	s_mov_b32 s4, 0x7f800000
	v_add_f32_e32 v2, v5, v2
	v_cmp_neq_f32_e64 s[4:5], s4, v4
	v_add_u32_e32 v3, -1, v201
	s_nop 0
	v_cndmask_b32_e64 v2, v202, v2, s[4:5]
	v_cmp_ngt_f32_e64 s[4:5], -1.0, v4
	s_nop 1
	v_cndmask_b32_e64 v2, v203, v2, s[4:5]
	v_cmp_neq_f32_e64 s[4:5], -1.0, v4
	s_nop 1
	v_cndmask_b32_e64 v2, v204, v2, s[4:5]
	s_mov_b32 s4, 0x33800000
	v_cmp_lt_f32_e64 s[4:5], |v4|, s4
	s_nop 1
	v_cndmask_b32_e64 v2, v2, v4, s[4:5]
	v_sub_f32_e32 v1, v1, v2
	v_mov_b32_e32 v4, v1
	s_nop 1
	v_add_f32_dpp v4, v1, v4 row_shr:1 row_mask:0xf bank_mask:0xf
	v_add_f32_dpp v4, v1, v4 row_shr:2 row_mask:0xf bank_mask:0xf
	v_add_f32_dpp v4, v1, v4 row_shr:3 row_mask:0xf bank_mask:0xf
	s_nop 1
	v_add_f32_dpp v4, v4, v4 row_shr:4 row_mask:0xf bank_mask:0xe
	s_nop 1
	v_add_f32_dpp v4, v4, v4 row_shr:8 row_mask:0xf bank_mask:0xc
	s_nop 1
	v_add_f32_dpp v4, v4, v4 row_bcast:15 row_mask:0xa bank_mask:0xf
	s_nop 1
	v_add_f32_dpp v4, v4, v4 row_bcast:31 row_mask:0xc bank_mask:0xf
	s_nop 0
	v_readlane_b32 s6, v4, 63
	s_nop 1
	v_mov_b32_e32 v1, s6
	v_sub_f32_e32 v2, v1, v4
	v_add_f32_e32 v2, v0, v2
	v_mov_b32_e32 v3, v2
	s_nop 1
	v_max_f32_dpp v3, v2, v3 row_shr:1 row_mask:0xf bank_mask:0xf
	v_max_f32_dpp v3, v2, v3 row_shr:2 row_mask:0xf bank_mask:0xf
	v_max_f32_dpp v3, v2, v3 row_shr:3 row_mask:0xf bank_mask:0xf
	s_nop 1
	v_max_f32_dpp v3, v3, v3 row_shr:4 row_mask:0xf bank_mask:0xe
	s_nop 1
	v_max_f32_dpp v3, v3, v3 row_shr:8 row_mask:0xf bank_mask:0xc
	s_nop 1
	v_max_f32_dpp v3, v3, v3 row_bcast:15 row_mask:0xa bank_mask:0xf
	s_nop 1
	v_max_f32_dpp v3, v3, v3 row_bcast:31 row_mask:0xc bank_mask:0xf
	s_nop 0
	v_readlane_b32 s7, v3, 63
	v_cmp_eq_u32_e64 s[4:5], 0, v14
	s_nop 1
	v_mov_b32_e32 v0, s7
	v_sub_f32_e32 v2, v2, v0
	v_mul_f32_e32 v2, 0x3fb8aa3b, v2
	v_exp_f32_e32 v2, v2
	v_lshl_add_u32 v3, v14, 2, 0
	ds_write_b32 v3, v2 offset:29952
	s_and_saveexec_b64 s[6:7], s[4:5]
	s_cbranch_execz .LBB0_291
	s_ashr_i32 s19, s18, 31
	s_lshl_b64 s[4:5], s[18:19], 2
	s_add_u32 s4, s24, s4
	s_addc_u32 s5, s25, s5
	global_store_dwordx2 v172, v[0:1], s[4:5]
